# P1 peeled first iteration: first two counted DMA waits relaxed to vmcnt(24) so epilogue stores drain under phases 1-2; first-unit prologue drains fully
# baseline (speedup 1.0000x reference)
; #define PG8_STAGE(bufoff, gbase, voff) do { _Pragma("unroll") for (int _i = 0; _i < 2; ++_i) \
;         __builtin_amdgcn_global_load_lds((const unsigned*)((const char*)(gbase) + (voff)[_i]), (PG8_LAS unsigned*)(lds + (bufoff) + ldsw + _i * 8192), 16, 0, 0); } while (0)
; #define PG8_WAIT_V(n) asm volatile("s_waitcnt vmcnt(" #n ")" ::: "memory")
; #define PG8_BAR __builtin_amdgcn_s_barrier()
; template <class Epi, class Sched, bool ALIGN_EPI>
; __device__ __forceinline__ unsigned long long gemm_phase(PG8_LAS unsigned char* lds, const Gemm g, const Sched& S, const Epi& E, const int probe_id) {
;     ...
;     const char* cA = (const char*)g.A + (size_t)cur.pm * tstepA + (size_t)cur.kp * K * 2; const char* cB = (const char*)g.Bt + (size_t)cur.pn * tstepB + (size_t)cur.kp * K * 2;
;     PG8_STAGE(PG8_SB(0, 0), cB, voffB); PG8_STAGE(PG8_SB(0, 1), cB + hstepB, voffB); PG8_STAGE(PG8_SA(0, 0), cA, voffA); PG8_STAGE(PG8_SA(0, 1), cA + hstepA, voffA);
;     if (wr == 1) PG8_BAR;
;     PG8_WAIT_V(2); PG8_BAR;
;     PG8_STAGE(PG8_SB(1, 0), cB + kstep, voffB); PG8_STAGE(PG8_SA(1, 0), cA + kstep, voffA); PG8_STAGE(PG8_SB(1, 1), cB + hstepB + kstep, voffB);
;     PG8_WAIT_V(6); PG8_BAR;
.LBB0_114:
	s_mov_b64 s[30:31], 0x80
	s_and_b32 s5, s11, 3
	s_add_i32 m0, s34, 0x18000
	v_lshl_add_u64 v[8:9], v[8:9], 0, s[30:31]
	s_lshl_b32 s92, s28, 6
	s_lshl_b32 s11, s28, 13
	s_lshl_b32 s50, s5, 12
	s_waitcnt vmcnt(2)
	s_barrier
	global_load_lds_dwordx4 v[8:9], off
	v_lshl_add_u64 v[6:7], v[6:7], 0, s[30:31]
	s_add_i32 m0, s34, 0x1a000
	s_add_i32 s95, s34, 0x8000
	s_add_i32 s97, s34, 0xa000
	global_load_lds_dwordx4 v[6:7], off
	v_lshl_add_u64 v[4:5], v[4:5], 0, s[30:31]
	s_mov_b32 m0, s95
	s_add_u32 s28, s8, 0x40080
	global_load_lds_dwordx4 v[4:5], off
	v_lshl_add_u64 v[4:5], v[10:11], 0, s[30:31]
	s_mov_b32 m0, s97
	s_addc_u32 s29, s9, 0
	global_load_lds_dwordx4 v[4:5], off
	s_add_i32 m0, s34, 0x1c000
	v_lshl_add_u64 v[4:5], s[28:29], 0, v[150:151]
	global_load_lds_dwordx4 v[4:5], off
	v_lshl_add_u64 v[4:5], s[28:29], 0, v[154:155]
	s_add_i32 m0, s34, 0x1e000
	v_and_b32_e32 v1, 15, v0
	global_load_lds_dwordx4 v[4:5], off
	v_lshlrev_b32_e32 v4, 1, v2
	v_lshlrev_b32_e32 v6, 2, v0
	v_lshl_or_b32 v5, v1, 6, v4
	v_and_b32_e32 v6, 32, v6
	v_bitop3_b32 v5, v5, s11, v6 bitop3:0xde
	v_lshlrev_b32_e32 v7, 6, v0
	s_movk_i32 s11, 0x3c0
	v_and_or_b32 v4, v7, s11, v4
	s_cmpk_lt_u32 s10, 0x100
	v_bitop3_b32 v147, s50, v4, v6 bitop3:0xf6
	s_cselect_b64 s[50:51], -1, 0
	s_ashr_i32 s10, s89, 31
	v_writelane_b32 v255, s10, 14
	s_and_b32 s10, s89, 7
	s_ashr_i32 s11, s89, 3
	s_mul_i32 s28, s10, 33
	s_and_b32 s29, s11, 7
	s_add_i32 s28, s29, s28
	v_writelane_b32 v255, s28, 15
	s_ashr_i32 s28, s89, 6
	v_writelane_b32 v255, s28, 16
	s_mul_i32 s28, s29, 33
	s_add_i32 s28, s28, 32
	s_and_b32 s11, s11, -8
	v_lshl_or_b32 v4, s5, 5, v2
	s_ashr_i32 s93, s33, 31
	v_writelane_b32 v255, s28, 17
	s_or_b32 s10, s11, s10
	v_or_b32_e32 v178, 0xfffff400, v4
	v_lshlrev_b32_e32 v4, 8, v0
	v_writelane_b32 v255, s10, 18
	s_add_u32 s10, s74, 0x3bc00000
	v_and_b32_e32 v4, 0x18000, v4
	v_lshlrev_b32_e32 v6, 11, v13
	s_addc_u32 s11, s75, 0
	v_or3_b32 v4, v3, v4, v6
	v_writelane_b32 v255, s10, 19
	v_add_u32_e32 v158, v4, v12
	v_lshlrev_b32_e32 v4, 4, v14
	v_writelane_b32 v255, s11, 20
	s_add_u32 s10, s74, 0x44000000
	v_and_b32_e32 v4, 0x38000, v4
	s_addc_u32 s11, s75, 0
	v_or3_b32 v3, v3, v4, v6
	v_writelane_b32 v255, s10, 21
	v_add_u32_e32 v160, v3, v12
	v_cndmask_b32_e64 v3, 0, 1, s[0:1]
	v_writelane_b32 v255, s11, 22
	v_cmp_ne_u32_e64 s[0:1], 1, v3
	s_waitcnt vmcnt(0)
	v_lshl_or_b32 v179, s5, 6, v2
	v_and_b32_e32 v237, 63, v0
	v_and_b32_e32 v238, 15, v237
	v_lshrrev_b32_e32 v239, 4, v237
	v_lshrrev_b32_e32 v240, 3, v237
	v_and_b32_e32 v241, 7, v237
	v_readfirstlane_b32 s100, v0
	s_nop 3
	s_lshr_b32 s100, s100, 6
	s_lshl_b32 s101, s100, 10
	s_add_i32 s101, s101, 0xc000
	v_and_b32_e32 v242, 7, v238
	v_lshrrev_b32_e32 v243, 3, v238
	v_lshlrev_b32_e32 v243, 13, v243
	v_lshl_add_u32 v243, v242, 7, v243
	v_add_u32_e32 v244, v239, v242
	v_and_b32_e32 v244, 7, v244
	v_lshl_add_u32 v232, v244, 4, v243
	v_add_u32_e32 v232, s101, v232
	v_add_u32_e32 v244, 4, v244
	v_and_b32_e32 v244, 7, v244
	v_lshl_add_u32 v233, v244, 4, v243
	v_add_u32_e32 v233, s101, v233
	v_add_u32_e32 v244, v241, v240
	v_and_b32_e32 v244, 7, v244
	v_lshlrev_b32_e32 v245, 7, v240
	v_lshl_add_u32 v234, v244, 4, v245
	v_add_u32_e32 v234, s101, v234
	s_mul_i32 s101, s100, 0x900
	s_add_i32 s101, s101, 0x21000
	v_mul_u32_u24_e32 v245, 0x90, v238
	v_lshl_add_u32 v235, v239, 5, v245
	v_add_u32_e32 v235, s101, v235
	v_mul_u32_u24_e32 v245, 0x90, v240
	v_lshl_add_u32 v236, v241, 4, v245
	v_add_u32_e32 v236, s101, v236
	v_sub_u32_e32 v245, v240, v238
	v_lshlrev_b32_e32 v245, 11, v245
	v_sub_u32_e32 v244, v241, v239
	v_lshl_add_u32 v250, v244, 4, v245
	v_ashrrev_i32_e32 v251, 31, v250
	v_lshlrev_b32_e32 v245, 1, v245
	v_lshl_add_u32 v252, v241, 4, v245
	v_lshlrev_b32_e32 v244, 5, v239
	v_sub_u32_e32 v252, v252, v244
	v_ashrrev_i32_e32 v253, 31, v252
	s_movk_i32 s98, 0x4000
	s_mov_b32 s99, 0
	s_mov_b32 s100, 0x8000
	s_mov_b32 s101, 0
	s_add_i32 s57, 0, 0x10000
	v_writelane_b32 v255, s0, 23
	s_add_i32 s60, 0, 0x14000
	v_lshlrev_b32_e32 v183, 2, v2
	v_writelane_b32 v255, s1, 24
	v_mbcnt_lo_u32_b32 v2, -1, 0
	v_mov_b32_e32 v159, v157
	v_mov_b32_e32 v161, v157
	v_add_u32_e32 v180, s57, v147
	v_add_u32_e32 v181, s60, v147
	v_add_u32_e32 v182, 0, v5
	v_mov_b32_e32 v184, 0x358637bd
	s_mov_b32 s61, 0xf800000
	v_mov_b32_e32 v185, 0x260
	v_mov_b64_e32 v[162:163], 0x20ff
	v_mov_b32_e32 v186, 0x3e38aa3b
	v_mbcnt_hi_u32_b32 v187, -1, v2
	v_writelane_b32 v255, s14, 25
	s_barrier
	s_branch .LBB0_117

; #define PG8_STAGE(bufoff, gbase, voff) do { _Pragma("unroll") for (int _i = 0; _i < 2; ++_i) \
;         __builtin_amdgcn_global_load_lds((const unsigned*)((const char*)(gbase) + (voff)[_i]), (PG8_LAS unsigned*)(lds + (bufoff) + ldsw + _i * 8192), 16, 0, 0); } while (0)
; #define PG8_LDA(dst, b, h) do { _Pragma("unroll") for (int m = 0; m < 4; ++m) _Pragma("unroll") for (int k = 0; k < 2; ++k) dst[m][k] = *(const PG8_LAS bf16x8*)(lds + PG8_SA(b, h) + aoff + m * 2048 + k * 1024); } while (0)
; #define PG8_LDB(dst, b, h) do { _Pragma("unroll") for (int n = 0; n < 2; ++n) _Pragma("unroll") for (int k = 0; k < 2; ++k) dst[n][k] = *(const PG8_LAS bf16x8*)(lds + PG8_SB(b, h) + boff + n * 2048 + k * 1024); } while (0)
; #define PG8_MMA(ai, bj, At, Bt) do { __builtin_amdgcn_s_setprio(1); _Pragma("unroll") for (int m = 0; m < 4; ++m) _Pragma("unroll") for (int n = 0; n < 2; ++n) _Pragma("unroll") for (int k = 0; k < 2; ++k) \
;         acc[ai][bj][m][n] = __builtin_amdgcn_mfma_f32_16x16x32_bf16(Bt[n][k], At[m][k], acc[ai][bj][m][n], 0, 0, 0); __builtin_amdgcn_s_setprio(0); } while (0)
; #define PG8_WAIT_V(n) asm volatile("s_waitcnt vmcnt(" #n ")" ::: "memory")
; #define PG8_BAR __builtin_amdgcn_s_barrier()
; template <class Epi, class Sched, bool ALIGN_EPI>
; __device__ __forceinline__ unsigned long long gemm_phase(PG8_LAS unsigned char* lds, const Gemm g, const Sched& S, const Epi& E, const int probe_id) {
;     ...
;         const char* nA = has_next ? (const char*)g.A + (size_t)nxt.pm * tstepA + (size_t)nxt.kp * K * 2 : cA; const char* nB = has_next ? (const char*)g.Bt + (size_t)nxt.pn * tstepB + (size_t)nxt.kp * K * 2 : cB;
;         for (int t = 0; t < nt; t += 2) {
;             const bool last = (t == nt - 2);
;             const char* a1 = cA + (size_t)(t + 1) * kstep;
;             const char* a2 = last ? nA : cA + (size_t)(t + 2) * kstep; const char* b2 = last ? nB : cB + (size_t)(t + 2) * kstep;
;             const char* a3 = a2 + kstep; const char* b3 = b2 + kstep;
;             PG8_LDB(B0, 0, 0); PG8_LDB(B1, 0, 1); PG8_SCHED; PG8_LDA(At, 0, 0); PG8_STAGE(PG8_SA(1, 1), a1 + hstepA, voffA);
;             PG8_WAIT_V(8); PG8_WAIT_L(0); PG8_BAR; PG8_MMA(0, 0, At, B0); PG8_MMA(0, 1, At, B1); PG8_BAR; PG8_SCHED;
;             PG8_LDA(At, 0, 1); PG8_STAGE(PG8_SB(0, 0), b2, voffB); PG8_STAGE(PG8_SB(0, 1), b2 + hstepB, voffB); PG8_STAGE(PG8_SA(0, 0), a2, voffA);
.LBB0_126:
	s_mov_b32 s68, s29
	s_ashr_i32 s69, s29, 31
	s_lshl_b64 s[10:11], s[68:69], 19
	s_add_u32 s80, s3, s10
	s_addc_u32 s81, s12, s11
	s_mov_b32 s70, s5
	s_and_b64 s[10:11], s[78:79], exec
	s_cselect_b32 s2, s81, s7
	s_cselect_b32 s5, s80, s6
	s_ashr_i32 s71, s70, 31
	s_lshl_b64 s[10:11], s[70:71], 19
	s_add_u32 s82, s13, s10
	s_addc_u32 s83, s14, s11
	s_and_b64 s[10:11], s[78:79], exec
	s_cselect_b32 s29, s83, s9
	s_cselect_b32 s56, s82, s8
	s_add_u32 s6, s6, 0x40080
	s_addc_u32 s7, s7, 0
	s_add_u32 s69, s8, 0x100
	s_addc_u32 s71, s9, 0
	s_mov_b32 s76, -2
	ds_read_b128 v[130:133], v180
	ds_read_b128 v[134:137], v180 offset:1024
	ds_read_b128 v[138:141], v180 offset:2048
	ds_read_b128 v[142:145], v180 offset:3072
	ds_read_b128 v[164:167], v181
	ds_read_b128 v[168:171], v181 offset:1024
	ds_read_b128 v[172:175], v181 offset:2048
	ds_read_b128 v[188:191], v181 offset:3072
	s_add_u32 s8, s6, 0xfffc0080
	s_addc_u32 s9, s7, -1
	s_cmp_eq_u32 s76, 12
	s_cselect_b32 s11, s2, s9
	s_cselect_b32 s10, s5, s8
	s_cselect_b32 s9, s29, s71
	s_cselect_b32 s8, s56, s69
	v_lshl_add_u64 v[176:177], s[6:7], 0, v[158:159]
	s_add_i32 m0, s34, 0xc000
	ds_read_b128 v[192:195], v182
	ds_read_b128 v[196:199], v182 offset:1024
	ds_read_b128 v[200:203], v182 offset:2048
	ds_read_b128 v[204:207], v182 offset:3072
	ds_read_b128 v[208:211], v182 offset:4096
	ds_read_b128 v[212:215], v182 offset:5120
	ds_read_b128 v[216:219], v182 offset:6144
	ds_read_b128 v[220:223], v182 offset:7168
	global_load_lds_dwordx4 v[176:177], off
	v_lshl_add_u64 v[176:177], s[6:7], 0, v[160:161]
	s_add_i32 m0, s34, 0xe000
	s_nop 0
	global_load_lds_dwordx4 v[176:177], off
	s_waitcnt vmcnt(24)
	s_waitcnt lgkmcnt(0)
	s_barrier
	s_setprio 1
	s_waitcnt lgkmcnt(0)
	v_mfma_f32_16x16x32_bf16 v[126:129], v[130:133], v[192:195], 0
	v_mfma_f32_16x16x32_bf16 v[122:125], v[138:141], v[192:195], 0
	v_mfma_f32_16x16x32_bf16 v[110:113], v[130:133], v[200:203], 0
	v_mfma_f32_16x16x32_bf16 v[106:109], v[138:141], v[200:203], 0
	v_mfma_f32_16x16x32_bf16 v[94:97], v[130:133], v[208:211], 0
	v_mfma_f32_16x16x32_bf16 v[90:93], v[138:141], v[208:211], 0
	v_mfma_f32_16x16x32_bf16 v[78:81], v[130:133], v[216:219], 0
	v_mfma_f32_16x16x32_bf16 v[74:77], v[138:141], v[216:219], 0
	v_mfma_f32_16x16x32_bf16 v[126:129], v[134:137], v[196:199], v[126:129]
	v_mfma_f32_16x16x32_bf16 v[122:125], v[142:145], v[196:199], v[122:125]
	v_mfma_f32_16x16x32_bf16 v[110:113], v[134:137], v[204:207], v[110:113]
	v_mfma_f32_16x16x32_bf16 v[106:109], v[142:145], v[204:207], v[106:109]
	v_mfma_f32_16x16x32_bf16 v[94:97], v[134:137], v[212:215], v[94:97]
	v_mfma_f32_16x16x32_bf16 v[90:93], v[142:145], v[212:215], v[90:93]
	v_mfma_f32_16x16x32_bf16 v[78:81], v[134:137], v[220:223], v[78:81]
	v_mfma_f32_16x16x32_bf16 v[74:77], v[142:145], v[220:223], v[74:77]
	s_setprio 0
	s_setprio 1
	v_mfma_f32_16x16x32_bf16 v[118:121], v[164:167], v[192:195], 0
	v_mfma_f32_16x16x32_bf16 v[114:117], v[172:175], v[192:195], 0
	v_mfma_f32_16x16x32_bf16 v[102:105], v[164:167], v[200:203], 0
	v_mfma_f32_16x16x32_bf16 v[98:101], v[172:175], v[200:203], 0
	v_mfma_f32_16x16x32_bf16 v[86:89], v[164:167], v[208:211], 0
	v_mfma_f32_16x16x32_bf16 v[82:85], v[172:175], v[208:211], 0
	v_mfma_f32_16x16x32_bf16 v[70:73], v[164:167], v[216:219], 0
	v_mfma_f32_16x16x32_bf16 v[66:69], v[172:175], v[216:219], 0
	v_mfma_f32_16x16x32_bf16 v[118:121], v[168:171], v[196:199], v[118:121]
	v_mfma_f32_16x16x32_bf16 v[114:117], v[188:191], v[196:199], v[114:117]
	v_mfma_f32_16x16x32_bf16 v[102:105], v[168:171], v[204:207], v[102:105]
	v_mfma_f32_16x16x32_bf16 v[98:101], v[188:191], v[204:207], v[98:101]
	v_mfma_f32_16x16x32_bf16 v[86:89], v[168:171], v[212:215], v[86:89]
	v_mfma_f32_16x16x32_bf16 v[82:85], v[188:191], v[212:215], v[82:85]
	v_mfma_f32_16x16x32_bf16 v[70:73], v[168:171], v[220:223], v[70:73]
	v_mfma_f32_16x16x32_bf16 v[66:69], v[188:191], v[220:223], v[66:69]
	s_setprio 0
	s_barrier
	s_add_i32 s86, s57, s15
	v_lshl_add_u64 v[176:177], s[8:9], 0, v[150:151]
	s_mov_b32 m0, s86
	ds_read_b128 v[192:195], v182 offset:16384
	ds_read_b128 v[196:199], v182 offset:17408
	ds_read_b128 v[200:203], v182 offset:18432
	ds_read_b128 v[204:207], v182 offset:19456
	ds_read_b128 v[208:211], v182 offset:20480
	ds_read_b128 v[212:215], v182 offset:21504
	ds_read_b128 v[216:219], v182 offset:22528
	ds_read_b128 v[220:223], v182 offset:23552
	global_load_lds_dwordx4 v[176:177], off
	s_add_i32 m0, s86, 0x2000
	s_add_u32 s86, s8, 0x40000
	v_lshl_add_u64 v[224:225], s[8:9], 0, v[154:155]
	s_addc_u32 s87, s9, 0
	s_add_i32 s88, s60, s15
	global_load_lds_dwordx4 v[224:225], off
	v_lshl_add_u64 v[226:227], s[86:87], 0, v[150:151]
	s_mov_b32 m0, s88
	v_lshl_add_u64 v[228:229], s[10:11], 0, v[152:153]
	global_load_lds_dwordx4 v[226:227], off
	v_lshl_add_u64 v[226:227], s[86:87], 0, v[154:155]
	s_add_i32 m0, s88, 0x2000
	s_nop 0
	global_load_lds_dwordx4 v[226:227], off
	v_lshl_add_u64 v[226:227], s[10:11], 0, v[148:149]
	s_mov_b32 m0, s34
	s_nop 0
	global_load_lds_dwordx4 v[226:227], off
	s_mov_b32 m0, s35
	s_nop 0
	global_load_lds_dwordx4 v[228:229], off
	s_waitcnt vmcnt(24)
	s_waitcnt lgkmcnt(0)
	s_barrier
; #define PG8_STAGE(bufoff, gbase, voff) do { _Pragma("unroll") for (int _i = 0; _i < 2; ++_i) \
;         __builtin_amdgcn_global_load_lds((const unsigned*)((const char*)(gbase) + (voff)[_i]), (PG8_LAS unsigned*)(lds + (bufoff) + ldsw + _i * 8192), 16, 0, 0); } while (0)
; #define PG8_LDA(dst, b, h) do { _Pragma("unroll") for (int m = 0; m < 4; ++m) _Pragma("unroll") for (int k = 0; k < 2; ++k) dst[m][k] = *(const PG8_LAS bf16x8*)(lds + PG8_SA(b, h) + aoff + m * 2048 + k * 1024); } while (0)
; #define PG8_LDB(dst, b, h) do { _Pragma("unroll") for (int n = 0; n < 2; ++n) _Pragma("unroll") for (int k = 0; k < 2; ++k) dst[n][k] = *(const PG8_LAS bf16x8*)(lds + PG8_SB(b, h) + boff + n * 2048 + k * 1024); } while (0)
; #define PG8_MMA(ai, bj, At, Bt) do { __builtin_amdgcn_s_setprio(1); _Pragma("unroll") for (int m = 0; m < 4; ++m) _Pragma("unroll") for (int n = 0; n < 2; ++n) _Pragma("unroll") for (int k = 0; k < 2; ++k) \
;         acc[ai][bj][m][n] = __builtin_amdgcn_mfma_f32_16x16x32_bf16(Bt[n][k], At[m][k], acc[ai][bj][m][n], 0, 0, 0); __builtin_amdgcn_s_setprio(0); } while (0)
; #define PG8_WAIT_V(n) asm volatile("s_waitcnt vmcnt(" #n ")" ::: "memory")
; #define PG8_WAIT_L(n) asm volatile("s_waitcnt lgkmcnt(" #n ")" ::: "memory")
; #define PG8_BAR __builtin_amdgcn_s_barrier()
; #define PG8_SCHED __builtin_amdgcn_sched_barrier(0)
; template <class Epi, class Sched, bool ALIGN_EPI>
; __device__ __forceinline__ unsigned long long gemm_phase(PG8_LAS unsigned char* lds, const Gemm g, const Sched& S, const Epi& E, const int probe_id) {
;     ...
;             PG8_LDA(At, 0, 1); PG8_STAGE(PG8_SB(0, 0), b2, voffB); PG8_STAGE(PG8_SB(0, 1), b2 + hstepB, voffB); PG8_STAGE(PG8_SA(0, 0), a2, voffA);
;             PG8_WAIT_V(8); PG8_WAIT_L(0); PG8_BAR; PG8_MMA(1, 0, At, B0); PG8_MMA(1, 1, At, B1); PG8_BAR; PG8_SCHED;
;             PG8_LDB(B0, 1, 0); PG8_LDB(B1, 1, 1); PG8_SCHED; PG8_LDA(At, 1, 0); PG8_STAGE(PG8_SA(0, 1), a2 + hstepA, voffA);
;             PG8_WAIT_V(8); PG8_WAIT_L(0); PG8_BAR; PG8_MMA(0, 0, At, B0); PG8_MMA(0, 1, At, B1); PG8_BAR; PG8_SCHED;
	s_setprio 1
	s_waitcnt lgkmcnt(0)
	v_mfma_f32_16x16x32_bf16 v[62:65], v[130:133], v[192:195], 0
	v_mfma_f32_16x16x32_bf16 v[58:61], v[138:141], v[192:195], 0
	v_mfma_f32_16x16x32_bf16 v[46:49], v[130:133], v[200:203], 0
	v_mfma_f32_16x16x32_bf16 v[42:45], v[138:141], v[200:203], 0
	v_mfma_f32_16x16x32_bf16 v[30:33], v[130:133], v[208:211], 0
	v_mfma_f32_16x16x32_bf16 v[26:29], v[138:141], v[208:211], 0
	v_mfma_f32_16x16x32_bf16 v[14:17], v[130:133], v[216:219], 0
	v_mfma_f32_16x16x32_bf16 v[10:13], v[138:141], v[216:219], 0
	v_mfma_f32_16x16x32_bf16 v[62:65], v[134:137], v[196:199], v[62:65]
	v_mfma_f32_16x16x32_bf16 v[58:61], v[142:145], v[196:199], v[58:61]
	v_mfma_f32_16x16x32_bf16 v[46:49], v[134:137], v[204:207], v[46:49]
	v_mfma_f32_16x16x32_bf16 v[42:45], v[142:145], v[204:207], v[42:45]
	v_mfma_f32_16x16x32_bf16 v[30:33], v[134:137], v[212:215], v[30:33]
	v_mfma_f32_16x16x32_bf16 v[26:29], v[142:145], v[212:215], v[26:29]
	v_mfma_f32_16x16x32_bf16 v[14:17], v[134:137], v[220:223], v[14:17]
	v_mfma_f32_16x16x32_bf16 v[10:13], v[142:145], v[220:223], v[10:13]
	s_setprio 0
	s_setprio 1
	v_mfma_f32_16x16x32_bf16 v[54:57], v[164:167], v[192:195], 0
	v_mfma_f32_16x16x32_bf16 v[50:53], v[172:175], v[192:195], 0
	v_mfma_f32_16x16x32_bf16 v[38:41], v[164:167], v[200:203], 0
	v_mfma_f32_16x16x32_bf16 v[34:37], v[172:175], v[200:203], 0
	v_mfma_f32_16x16x32_bf16 v[22:25], v[164:167], v[208:211], 0
	v_mfma_f32_16x16x32_bf16 v[18:21], v[172:175], v[208:211], 0
	v_mfma_f32_16x16x32_bf16 v[6:9], v[164:167], v[216:219], 0
	v_mfma_f32_16x16x32_bf16 v[2:5], v[172:175], v[216:219], 0
	v_mfma_f32_16x16x32_bf16 v[54:57], v[168:171], v[196:199], v[54:57]
	v_mfma_f32_16x16x32_bf16 v[50:53], v[188:191], v[196:199], v[50:53]
	v_mfma_f32_16x16x32_bf16 v[38:41], v[168:171], v[204:207], v[38:41]
	v_mfma_f32_16x16x32_bf16 v[34:37], v[188:191], v[204:207], v[34:37]
	v_mfma_f32_16x16x32_bf16 v[22:25], v[168:171], v[212:215], v[22:25]
	v_mfma_f32_16x16x32_bf16 v[18:21], v[188:191], v[212:215], v[18:21]
	v_mfma_f32_16x16x32_bf16 v[6:9], v[168:171], v[220:223], v[6:9]
	v_mfma_f32_16x16x32_bf16 v[2:5], v[188:191], v[220:223], v[2:5]
	s_setprio 0
	s_barrier
	s_add_i32 s86, 0, 0x18000
	s_add_i32 s87, 0, 0x1c000
	v_add_u32_e32 v142, s86, v147
	v_add_u32_e32 v156, s87, v147
	ds_read_b128 v[130:133], v142
	ds_read_b128 v[134:137], v142 offset:1024
	ds_read_b128 v[138:141], v142 offset:2048
	ds_read_b128 v[142:145], v142 offset:3072
	ds_read_b128 v[164:167], v156
	ds_read_b128 v[168:171], v156 offset:1024
	ds_read_b128 v[172:175], v156 offset:2048
	ds_read_b128 v[188:191], v156 offset:3072
	s_add_u32 s10, s10, 0x40000
	s_addc_u32 s11, s11, 0
	s_mov_b32 m0, s77
	v_lshl_add_u64 v[230:231], s[10:11], 0, v[148:149]
	ds_read_b128 v[192:195], v182 offset:32768
	ds_read_b128 v[196:199], v182 offset:33792
	ds_read_b128 v[200:203], v182 offset:34816
	ds_read_b128 v[204:207], v182 offset:35840
	ds_read_b128 v[208:211], v182 offset:36864
	ds_read_b128 v[212:215], v182 offset:37888
	ds_read_b128 v[216:219], v182 offset:38912
	ds_read_b128 v[220:223], v182 offset:39936
	global_load_lds_dwordx4 v[230:231], off
	v_lshl_add_u64 v[230:231], s[10:11], 0, v[152:153]
	s_mov_b32 m0, s85
	s_nop 0
	global_load_lds_dwordx4 v[230:231], off
	s_waitcnt vmcnt(8)
	s_waitcnt lgkmcnt(0)
	s_barrier
	s_setprio 1
	s_waitcnt lgkmcnt(0)
	v_mfma_f32_16x16x32_bf16 v[126:129], v[130:133], v[192:195], v[126:129]
	v_mfma_f32_16x16x32_bf16 v[122:125], v[138:141], v[192:195], v[122:125]
	v_mfma_f32_16x16x32_bf16 v[110:113], v[130:133], v[200:203], v[110:113]
	v_mfma_f32_16x16x32_bf16 v[106:109], v[138:141], v[200:203], v[106:109]
	v_mfma_f32_16x16x32_bf16 v[94:97], v[130:133], v[208:211], v[94:97]
	v_mfma_f32_16x16x32_bf16 v[90:93], v[138:141], v[208:211], v[90:93]
	v_mfma_f32_16x16x32_bf16 v[78:81], v[130:133], v[216:219], v[78:81]
	v_mfma_f32_16x16x32_bf16 v[74:77], v[138:141], v[216:219], v[74:77]
	v_mfma_f32_16x16x32_bf16 v[126:129], v[134:137], v[196:199], v[126:129]
	v_mfma_f32_16x16x32_bf16 v[122:125], v[142:145], v[196:199], v[122:125]
	v_mfma_f32_16x16x32_bf16 v[110:113], v[134:137], v[204:207], v[110:113]
	v_mfma_f32_16x16x32_bf16 v[106:109], v[142:145], v[204:207], v[106:109]
	v_mfma_f32_16x16x32_bf16 v[94:97], v[134:137], v[212:215], v[94:97]
	v_mfma_f32_16x16x32_bf16 v[90:93], v[142:145], v[212:215], v[90:93]
	v_mfma_f32_16x16x32_bf16 v[78:81], v[134:137], v[220:223], v[78:81]
	v_mfma_f32_16x16x32_bf16 v[74:77], v[142:145], v[220:223], v[74:77]
	s_setprio 0
	s_setprio 1
	v_mfma_f32_16x16x32_bf16 v[118:121], v[164:167], v[192:195], v[118:121]
	v_mfma_f32_16x16x32_bf16 v[114:117], v[172:175], v[192:195], v[114:117]
	v_mfma_f32_16x16x32_bf16 v[102:105], v[164:167], v[200:203], v[102:105]
	v_mfma_f32_16x16x32_bf16 v[98:101], v[172:175], v[200:203], v[98:101]
	v_mfma_f32_16x16x32_bf16 v[86:89], v[164:167], v[208:211], v[86:89]
	v_mfma_f32_16x16x32_bf16 v[82:85], v[172:175], v[208:211], v[82:85]
	v_mfma_f32_16x16x32_bf16 v[70:73], v[164:167], v[216:219], v[70:73]
	v_mfma_f32_16x16x32_bf16 v[66:69], v[172:175], v[216:219], v[66:69]
	v_mfma_f32_16x16x32_bf16 v[118:121], v[168:171], v[196:199], v[118:121]
	v_mfma_f32_16x16x32_bf16 v[114:117], v[188:191], v[196:199], v[114:117]
	v_mfma_f32_16x16x32_bf16 v[102:105], v[168:171], v[204:207], v[102:105]
	v_mfma_f32_16x16x32_bf16 v[98:101], v[188:191], v[204:207], v[98:101]
	v_mfma_f32_16x16x32_bf16 v[86:89], v[168:171], v[212:215], v[86:89]
	v_mfma_f32_16x16x32_bf16 v[82:85], v[188:191], v[212:215], v[82:85]
	v_mfma_f32_16x16x32_bf16 v[70:73], v[168:171], v[220:223], v[70:73]
	v_mfma_f32_16x16x32_bf16 v[66:69], v[188:191], v[220:223], v[66:69]
	s_setprio 0
	s_barrier
; #define PG8_STAGE(bufoff, gbase, voff) do { _Pragma("unroll") for (int _i = 0; _i < 2; ++_i) \
;         __builtin_amdgcn_global_load_lds((const unsigned*)((const char*)(gbase) + (voff)[_i]), (PG8_LAS unsigned*)(lds + (bufoff) + ldsw + _i * 8192), 16, 0, 0); } while (0)
; #define PG8_LDA(dst, b, h) do { _Pragma("unroll") for (int m = 0; m < 4; ++m) _Pragma("unroll") for (int k = 0; k < 2; ++k) dst[m][k] = *(const PG8_LAS bf16x8*)(lds + PG8_SA(b, h) + aoff + m * 2048 + k * 1024); } while (0)
; #define PG8_MMA(ai, bj, At, Bt) do { __builtin_amdgcn_s_setprio(1); _Pragma("unroll") for (int m = 0; m < 4; ++m) _Pragma("unroll") for (int n = 0; n < 2; ++n) _Pragma("unroll") for (int k = 0; k < 2; ++k) \
;         acc[ai][bj][m][n] = __builtin_amdgcn_mfma_f32_16x16x32_bf16(Bt[n][k], At[m][k], acc[ai][bj][m][n], 0, 0, 0); __builtin_amdgcn_s_setprio(0); } while (0)
; #define PG8_WAIT_V(n) asm volatile("s_waitcnt vmcnt(" #n ")" ::: "memory")
; #define PG8_WAIT_L(n) asm volatile("s_waitcnt lgkmcnt(" #n ")" ::: "memory")
; #define PG8_BAR __builtin_amdgcn_s_barrier()
; #define PG8_SCHED __builtin_amdgcn_sched_barrier(0)
; template <class Epi, class Sched, bool ALIGN_EPI>
; __device__ __forceinline__ unsigned long long gemm_phase(PG8_LAS unsigned char* lds, const Gemm g, const Sched& S, const Epi& E, const int probe_id) {
;     ...
;             PG8_LDA(At, 1, 1); PG8_STAGE(PG8_SB(1, 0), b3, voffB); PG8_STAGE(PG8_SB(1, 1), b3 + hstepB, voffB); PG8_STAGE(PG8_SA(1, 0), a3, voffA);
;             PG8_WAIT_V(8); PG8_WAIT_L(0); PG8_BAR; PG8_MMA(1, 0, At, B0); PG8_MMA(1, 1, At, B1); PG8_BAR; PG8_SCHED;
	s_add_i32 s10, s86, s15
	v_lshl_add_u64 v[176:177], v[176:177], 0, s[30:31]
	s_mov_b32 m0, s10
	ds_read_b128 v[192:195], v182 offset:49152
	ds_read_b128 v[196:199], v182 offset:50176
	ds_read_b128 v[200:203], v182 offset:51200
	ds_read_b128 v[204:207], v182 offset:52224
	ds_read_b128 v[208:211], v182 offset:53248
	ds_read_b128 v[212:215], v182 offset:54272
	ds_read_b128 v[216:219], v182 offset:55296
	ds_read_b128 v[220:223], v182 offset:56320
	global_load_lds_dwordx4 v[176:177], off
	s_add_i32 m0, s10, 0x2000
	s_add_u32 s8, s8, 0x40080
	v_lshl_add_u64 v[176:177], v[224:225], 0, s[30:31]
	s_addc_u32 s9, s9, 0
	s_add_i32 s10, s87, s15
	global_load_lds_dwordx4 v[176:177], off
	v_lshl_add_u64 v[176:177], s[8:9], 0, v[150:151]
	s_mov_b32 m0, s10
	s_nop 0
	global_load_lds_dwordx4 v[176:177], off
	v_lshl_add_u64 v[176:177], s[8:9], 0, v[154:155]
	s_add_i32 m0, s10, 0x2000
	s_nop 0
	global_load_lds_dwordx4 v[176:177], off
	v_lshl_add_u64 v[176:177], v[226:227], 0, s[30:31]
	s_mov_b32 m0, s95
	s_nop 0
	global_load_lds_dwordx4 v[176:177], off
	v_lshl_add_u64 v[176:177], v[228:229], 0, s[30:31]
	s_mov_b32 m0, s97
	s_nop 0
	global_load_lds_dwordx4 v[176:177], off
	s_waitcnt vmcnt(8)
	s_waitcnt lgkmcnt(0)
	s_barrier
	s_setprio 1
	s_waitcnt lgkmcnt(0)
	v_mfma_f32_16x16x32_bf16 v[62:65], v[130:133], v[192:195], v[62:65]
	v_mfma_f32_16x16x32_bf16 v[58:61], v[138:141], v[192:195], v[58:61]
	v_mfma_f32_16x16x32_bf16 v[46:49], v[130:133], v[200:203], v[46:49]
	v_mfma_f32_16x16x32_bf16 v[42:45], v[138:141], v[200:203], v[42:45]
	v_mfma_f32_16x16x32_bf16 v[30:33], v[130:133], v[208:211], v[30:33]
	v_mfma_f32_16x16x32_bf16 v[26:29], v[138:141], v[208:211], v[26:29]
	v_mfma_f32_16x16x32_bf16 v[14:17], v[130:133], v[216:219], v[14:17]
	v_mfma_f32_16x16x32_bf16 v[10:13], v[138:141], v[216:219], v[10:13]
	v_mfma_f32_16x16x32_bf16 v[62:65], v[134:137], v[196:199], v[62:65]
	v_mfma_f32_16x16x32_bf16 v[58:61], v[142:145], v[196:199], v[58:61]
	v_mfma_f32_16x16x32_bf16 v[46:49], v[134:137], v[204:207], v[46:49]
	v_mfma_f32_16x16x32_bf16 v[42:45], v[142:145], v[204:207], v[42:45]
	v_mfma_f32_16x16x32_bf16 v[30:33], v[134:137], v[212:215], v[30:33]
	v_mfma_f32_16x16x32_bf16 v[26:29], v[142:145], v[212:215], v[26:29]
	v_mfma_f32_16x16x32_bf16 v[14:17], v[134:137], v[220:223], v[14:17]
	v_mfma_f32_16x16x32_bf16 v[10:13], v[142:145], v[220:223], v[10:13]
	s_setprio 0
	s_setprio 1
	v_mfma_f32_16x16x32_bf16 v[54:57], v[164:167], v[192:195], v[54:57]
	v_mfma_f32_16x16x32_bf16 v[50:53], v[172:175], v[192:195], v[50:53]
	v_mfma_f32_16x16x32_bf16 v[38:41], v[164:167], v[200:203], v[38:41]
	v_mfma_f32_16x16x32_bf16 v[34:37], v[172:175], v[200:203], v[34:37]
	v_mfma_f32_16x16x32_bf16 v[22:25], v[164:167], v[208:211], v[22:25]
	v_mfma_f32_16x16x32_bf16 v[18:21], v[172:175], v[208:211], v[18:21]
	v_mfma_f32_16x16x32_bf16 v[6:9], v[164:167], v[216:219], v[6:9]
	v_mfma_f32_16x16x32_bf16 v[2:5], v[172:175], v[216:219], v[2:5]
	v_mfma_f32_16x16x32_bf16 v[54:57], v[168:171], v[196:199], v[54:57]
	v_mfma_f32_16x16x32_bf16 v[50:53], v[188:191], v[196:199], v[50:53]
	v_mfma_f32_16x16x32_bf16 v[38:41], v[168:171], v[204:207], v[38:41]
	v_mfma_f32_16x16x32_bf16 v[34:37], v[188:191], v[204:207], v[34:37]
	v_mfma_f32_16x16x32_bf16 v[22:25], v[168:171], v[212:215], v[22:25]
	v_mfma_f32_16x16x32_bf16 v[18:21], v[188:191], v[212:215], v[18:21]
	v_mfma_f32_16x16x32_bf16 v[6:9], v[168:171], v[220:223], v[6:9]
	v_mfma_f32_16x16x32_bf16 v[2:5], v[188:191], v[220:223], v[2:5]
	s_setprio 0
	s_barrier
	s_add_i32 s76, s76, 2
	s_add_u32 s6, s6, 0x100
	s_addc_u32 s7, s7, 0
	s_add_u32 s69, s69, 0x100
	s_addc_u32 s71, s71, 0
